# all four 8-deep LDS read->MFMA chains of the mLSTM output unit issue their reads up front (address temps in the destination quads) and wait progressively
# baseline (speedup 1.0000x reference)
.LBB0_672:
	s_and_b32 s0, s95, 0x3fffffc0
	s_lshl_b32 s0, s0, 2
	s_add_i32 s6, s0, 0
	s_ashr_i32 s39, s38, 31
	s_add_i32 s6, s6, 0x21000
	s_lshl_b64 s[0:1], s[38:39], 2
	s_add_u32 s0, s20, s0
	s_addc_u32 s1, s21, s1
	global_load_dword v34, v179, s[0:1]
	v_and_b32_e32 v135, 31, v168
	v_lshrrev_b32_e32 v136, 5, v171
	v_lshl_or_b32 v141, s61, 5, v135
	v_lshlrev_b32_e32 v66, 4, v136
	v_lshlrev_b32_e32 v35, 4, v168
	s_movk_i32 s0, 0xf0
	v_and_b32_e32 v36, 0xf0, v35
	v_lshl_add_u32 v37, v141, 8, 0
	v_bitop3_b32 v147, v66, v35, s0 bitop3:0x78
	v_add_u32_e32 v35, v37, v147
	v_bitop3_b32 v148, v66, v36, 32 bitop3:0x36
	v_bitop3_b32 v149, v66, v36, 64 bitop3:0x36
	s_movk_i32 s0, 0xa0
	s_waitcnt lgkmcnt(0)
	s_barrier
	v_add_u32_e32 v38, v37, v148
	ds_read_b128 v[110:113], v35
	ds_read_b128 v[106:109], v38
	v_add_u32_e32 v35, v37, v149
	v_bitop3_b32 v150, v66, v36, s64 bitop3:0x36
	v_bitop3_b32 v151, v66, v36, s96 bitop3:0x36
	v_bitop3_b32 v152, v66, v36, s0 bitop3:0x36
	s_movk_i32 s0, 0xc0
	v_add_u32_e32 v38, v37, v150
	ds_read_b128 v[102:105], v35
	ds_read_b128 v[94:97], v38
	v_add_u32_e32 v35, v37, v151
	v_bitop3_b32 v153, v66, v36, s0 bitop3:0x36
	s_movk_i32 s0, 0xe0
	v_add_u32_e32 v38, v37, v152
	ds_read_b128 v[98:101], v35
	ds_read_b128 v[86:89], v38
	v_add_u32_e32 v35, v37, v153
	v_bitop3_b32 v155, v66, v36, s0 bitop3:0x36
	v_add_u32_e32 v36, v37, v155
	ds_read_b128 v[90:93], v35
	ds_read_b128 v[82:85], v36
	v_lshlrev_b32_e32 v35, 1, v170
	v_and_b32_e32 v35, 8, v35
	v_and_or_b32 v38, v170, 48, v35
	v_lshrrev_b32_e32 v36, 1, v170
	v_bfe_u32 v37, v168, 4, 2
	v_lshrrev_b32_e32 v38, 1, v38
	v_and_or_b32 v36, v36, 4, v37
	v_lshlrev_b32_e32 v37, 8, v170
	v_or_b32_e32 v38, v38, v50
	v_lshl_or_b32 v36, v36, 6, v51
	v_and_b32_e32 v37, 0xffffc000, v37
	v_lshlrev_b32_e32 v38, 9, v38
	v_or3_b32 v39, v36, v37, v38
	s_add_i32 s7, 0, 0x18000
	v_add_u32_e32 v40, s7, v39
	s_waitcnt lgkmcnt(0)
	s_waitcnt lgkmcnt(0)
	s_barrier
	ds_write_b128 v40, v[14:17]
	v_add_u32_e32 v14, 0, v39
	ds_write_b128 v14, v[30:33]
	v_add_u32_e32 v14, 32, v170
	v_lshlrev_b32_e32 v15, 8, v14
	v_and_or_b32 v14, v14, 48, v35
	v_lshrrev_b32_e32 v14, 1, v14
	v_or_b32_e32 v14, v14, v50
	v_and_b32_e32 v15, 0xffffc000, v15
	v_lshlrev_b32_e32 v14, 9, v14
	v_or3_b32 v14, v14, v15, v36
	v_add_u32_e32 v15, s7, v14
	ds_write_b128 v15, v[6:9]
	v_add_u32_e32 v6, 0, v14
	ds_write_b128 v6, v[26:29]
	v_or3_b32 v6, v38, v37, v36
	v_add_u32_e32 v7, s7, v6
	v_add_u32_e32 v6, 0, v6
	ds_write_b128 v7, v[10:13] offset:16384
	ds_write_b128 v6, v[22:25] offset:16384
	v_add_u32_e32 v6, 0x60, v170
	v_lshlrev_b32_e32 v7, 8, v6
	v_and_or_b32 v6, v6, 48, v35
	v_lshrrev_b32_e32 v6, 1, v6
	v_or_b32_e32 v6, v6, v50
	v_and_b32_e32 v7, 0xffffc000, v7
	v_lshlrev_b32_e32 v6, 9, v6
	v_or3_b32 v6, v6, v7, v36
	v_add_u32_e32 v7, s7, v6
	ds_write_b128 v7, v[2:5]
	v_add_u32_e32 v2, 0, v6
	ds_write_b128 v2, v[18:21]
	v_lshl_add_u32 v2, v141, 2, s94
	s_waitcnt lgkmcnt(0)
	s_barrier
	ds_read2st64_b32 v[2:3], v2 offset1:4
	v_and_b32_e32 v14, 0xffff0000, v110
	v_lshlrev_b32_e32 v13, 16, v110
	v_and_b32_e32 v15, 0xffff0000, v106
	v_cmp_gt_u32_e64 s[4:5], 32, v171
	s_waitcnt lgkmcnt(0)
	v_add_f32_e32 v3, v2, v3
	s_waitcnt vmcnt(0)
	v_add_f32_e32 v4, v34, v2
	v_max_f32_e32 v137, v3, v4
	v_sub_f32_e32 v3, v4, v137
	v_and_b32_e32 v4, 32, v168
	v_add_u32_e32 v12, s94, v4
	ds_read_b128 v[4:7], v12 offset:1536
	ds_read_b128 v[8:11], v12 offset:1552
	v_mul_f32_e32 v3, 0x3fb8aa3b, v3
	v_exp_f32_e32 v139, v3
	v_lshl_add_u32 v138, v135, 2, s6
	s_waitcnt lgkmcnt(1)
	v_mul_f32_e32 v14, v5, v14
	v_fmac_f32_e32 v14, v4, v13
	v_lshlrev_b32_e32 v4, 16, v111
	v_fmac_f32_e32 v14, v6, v4
	v_and_b32_e32 v4, 0xffff0000, v111
	v_fmac_f32_e32 v14, v7, v4
	v_lshlrev_b32_e32 v4, 16, v112
	s_waitcnt lgkmcnt(0)
	v_fmac_f32_e32 v14, v8, v4
	v_and_b32_e32 v4, 0xffff0000, v112
	v_fmac_f32_e32 v14, v9, v4
	v_lshlrev_b32_e32 v4, 16, v113
	v_fmac_f32_e32 v14, v10, v4
	v_and_b32_e32 v4, 0xffff0000, v113
	v_fmac_f32_e32 v14, v11, v4
	ds_read_b128 v[4:7], v12 offset:1600
	ds_read_b128 v[8:11], v12 offset:1616
	v_add_f32_e32 v13, 0, v14
	v_lshlrev_b32_e32 v14, 16, v106
	s_waitcnt lgkmcnt(1)
	v_mul_f32_e32 v15, v5, v15
	v_fmac_f32_e32 v15, v4, v14
	v_lshlrev_b32_e32 v4, 16, v107
	v_fmac_f32_e32 v15, v6, v4
	v_and_b32_e32 v4, 0xffff0000, v107
	v_fmac_f32_e32 v15, v7, v4
	v_lshlrev_b32_e32 v4, 16, v108
	s_waitcnt lgkmcnt(0)
	v_fmac_f32_e32 v15, v8, v4
	v_and_b32_e32 v4, 0xffff0000, v108
	v_fmac_f32_e32 v15, v9, v4
	v_lshlrev_b32_e32 v4, 16, v109
	v_fmac_f32_e32 v15, v10, v4
	v_and_b32_e32 v4, 0xffff0000, v109
	v_fmac_f32_e32 v15, v11, v4
	ds_read_b128 v[4:7], v12 offset:1664
	ds_read_b128 v[8:11], v12 offset:1680
	v_add_f32_e32 v13, v13, v15
	v_and_b32_e32 v15, 0xffff0000, v102
	v_lshlrev_b32_e32 v14, 16, v102
	s_waitcnt lgkmcnt(1)
	v_mul_f32_e32 v15, v5, v15
	v_fmac_f32_e32 v15, v4, v14
	v_lshlrev_b32_e32 v4, 16, v103
	v_fmac_f32_e32 v15, v6, v4
	v_and_b32_e32 v4, 0xffff0000, v103
	v_fmac_f32_e32 v15, v7, v4
	v_lshlrev_b32_e32 v4, 16, v104
	s_waitcnt lgkmcnt(0)
	v_fmac_f32_e32 v15, v8, v4
	v_and_b32_e32 v4, 0xffff0000, v104
	v_fmac_f32_e32 v15, v9, v4
	v_lshlrev_b32_e32 v4, 16, v105
	v_fmac_f32_e32 v15, v10, v4
	v_and_b32_e32 v4, 0xffff0000, v105
	v_fmac_f32_e32 v15, v11, v4
	ds_read_b128 v[4:7], v12 offset:1728
	ds_read_b128 v[8:11], v12 offset:1744
	v_add_f32_e32 v13, v13, v15
	v_and_b32_e32 v15, 0xffff0000, v94
	v_lshlrev_b32_e32 v14, 16, v94
	s_waitcnt lgkmcnt(1)
	v_mul_f32_e32 v15, v5, v15
	v_fmac_f32_e32 v15, v4, v14
	v_lshlrev_b32_e32 v4, 16, v95
	v_fmac_f32_e32 v15, v6, v4
	v_and_b32_e32 v4, 0xffff0000, v95
	v_fmac_f32_e32 v15, v7, v4
	v_lshlrev_b32_e32 v4, 16, v96
	s_waitcnt lgkmcnt(0)
	v_fmac_f32_e32 v15, v8, v4
	v_and_b32_e32 v4, 0xffff0000, v96
	v_fmac_f32_e32 v15, v9, v4
	v_lshlrev_b32_e32 v4, 16, v97
	v_fmac_f32_e32 v15, v10, v4
	v_and_b32_e32 v4, 0xffff0000, v97
	v_fmac_f32_e32 v15, v11, v4
	ds_read_b128 v[4:7], v12 offset:1792
	ds_read_b128 v[8:11], v12 offset:1808
	v_add_f32_e32 v13, v13, v15
	v_and_b32_e32 v15, 0xffff0000, v98
	v_lshlrev_b32_e32 v14, 16, v98
	s_waitcnt lgkmcnt(1)
	v_mul_f32_e32 v15, v5, v15
	v_fmac_f32_e32 v15, v4, v14
	v_lshlrev_b32_e32 v4, 16, v99
	v_fmac_f32_e32 v15, v6, v4
	v_and_b32_e32 v4, 0xffff0000, v99
	v_fmac_f32_e32 v15, v7, v4
	v_lshlrev_b32_e32 v4, 16, v100
	s_waitcnt lgkmcnt(0)
	v_fmac_f32_e32 v15, v8, v4
	v_and_b32_e32 v4, 0xffff0000, v100
	v_fmac_f32_e32 v15, v9, v4
	v_lshlrev_b32_e32 v4, 16, v101
	v_fmac_f32_e32 v15, v10, v4
	v_and_b32_e32 v4, 0xffff0000, v101
	v_fmac_f32_e32 v15, v11, v4
	ds_read_b128 v[4:7], v12 offset:1856
	ds_read_b128 v[8:11], v12 offset:1872
	v_add_f32_e32 v13, v13, v15
	v_and_b32_e32 v15, 0xffff0000, v86
	v_lshlrev_b32_e32 v14, 16, v86
	s_waitcnt lgkmcnt(1)
	v_mul_f32_e32 v15, v5, v15
	v_fmac_f32_e32 v15, v4, v14
	v_lshlrev_b32_e32 v4, 16, v87
	v_fmac_f32_e32 v15, v6, v4
	v_and_b32_e32 v4, 0xffff0000, v87
	v_fmac_f32_e32 v15, v7, v4
	v_lshlrev_b32_e32 v4, 16, v88
	s_waitcnt lgkmcnt(0)
	v_fmac_f32_e32 v15, v8, v4
	v_and_b32_e32 v4, 0xffff0000, v88
	v_fmac_f32_e32 v15, v9, v4
	v_lshlrev_b32_e32 v4, 16, v89
	v_fmac_f32_e32 v15, v10, v4
	v_and_b32_e32 v4, 0xffff0000, v89
	v_fmac_f32_e32 v15, v11, v4
	ds_read_b128 v[4:7], v12 offset:1920
	ds_read_b128 v[8:11], v12 offset:1936
	v_add_f32_e32 v13, v13, v15
	v_and_b32_e32 v15, 0xffff0000, v90
	v_lshlrev_b32_e32 v14, 16, v90
	s_waitcnt lgkmcnt(1)
	v_mul_f32_e32 v15, v5, v15
	v_fmac_f32_e32 v15, v4, v14
	v_lshlrev_b32_e32 v4, 16, v91
	v_fmac_f32_e32 v15, v6, v4
	v_and_b32_e32 v4, 0xffff0000, v91
	v_fmac_f32_e32 v15, v7, v4
	v_lshlrev_b32_e32 v4, 16, v92
	s_waitcnt lgkmcnt(0)
	v_fmac_f32_e32 v15, v8, v4
	v_and_b32_e32 v4, 0xffff0000, v92
	v_fmac_f32_e32 v15, v9, v4
	v_lshlrev_b32_e32 v4, 16, v93
	v_fmac_f32_e32 v15, v10, v4
	v_and_b32_e32 v4, 0xffff0000, v93
	v_fmac_f32_e32 v15, v11, v4
	ds_read_b128 v[4:7], v12 offset:1984
	ds_read_b128 v[8:11], v12 offset:2000
	v_add_f32_e32 v13, v13, v15
	v_and_b32_e32 v15, 0xffff0000, v82
	v_lshlrev_b32_e32 v14, 16, v82
	s_waitcnt lgkmcnt(1)
	v_mul_f32_e32 v5, v5, v15
	v_fmac_f32_e32 v5, v4, v14
	v_lshlrev_b32_e32 v4, 16, v83
	v_fmac_f32_e32 v5, v6, v4
	v_and_b32_e32 v4, 0xffff0000, v83
	v_fmac_f32_e32 v5, v7, v4
	v_lshlrev_b32_e32 v4, 16, v84
	s_waitcnt lgkmcnt(0)
	v_fmac_f32_e32 v5, v8, v4
	v_and_b32_e32 v4, 0xffff0000, v84
	v_fmac_f32_e32 v5, v9, v4
	v_lshlrev_b32_e32 v4, 16, v85
	v_fmac_f32_e32 v5, v10, v4
	v_and_b32_e32 v4, 0xffff0000, v85
	v_fmac_f32_e32 v5, v11, v4
	v_add_f32_e32 v140, v13, v5
	v_mov_b32_e32 v142, v140
	s_nop 1
	v_permlane32_swap_b32_e32 v140, v142
	s_and_saveexec_b64 s[0:1], s[4:5]
	ds_write_b32 v138, v139
	s_or_b64 exec, exec, s[0:1]
	v_lshlrev_b32_e32 v4, 4, v171
	v_lshlrev_b32_e32 v3, 3, v171
	v_and_b32_e32 v4, 0xc0, v4
	v_lshlrev_b32_e32 v5, 1, v171
	v_and_or_b32 v4, v3, 24, v4
	v_and_b32_e32 v5, 32, v5
	v_and_b32_e32 v3, 0x100, v3
	s_and_b64 s[0:1], s[14:15], exec
	v_or3_b32 v143, v4, v5, v3
	s_cselect_b32 s0, s7, 0
	v_sub_f32_e32 v145, v2, v137
	v_add_u32_e32 v67, s0, v143
	ds_read_b64_tr_b16 v[2:3], v67 offset:0
	ds_read_b64_tr_b16 v[4:5], v67 offset:0x800
	ds_read_b64_tr_b16 v[18:19], v67 offset:0x1000
	ds_read_b64_tr_b16 v[20:21], v67 offset:0x1800
	ds_read_b64_tr_b16 v[22:23], v67 offset:0x2000
	ds_read_b64_tr_b16 v[24:25], v67 offset:0x2800
	ds_read_b64_tr_b16 v[26:27], v67 offset:0x3000
	ds_read_b64_tr_b16 v[28:29], v67 offset:0x3800
	s_nop 0
	s_waitcnt lgkmcnt(6)
	ds_read_b64_tr_b16 v[30:31], v67 offset:0x200
	ds_read_b64_tr_b16 v[32:33], v67 offset:0xa00
	s_waitcnt lgkmcnt(6)
	ds_read_b64_tr_b16 v[34:35], v67 offset:0x1200
	ds_read_b64_tr_b16 v[36:37], v67 offset:0x1a00
	s_nop 0
	v_mfma_f32_32x32x16_bf16 v[2:17], v[110:113], v[2:5], 0
	s_waitcnt lgkmcnt(6)
	ds_read_b64_tr_b16 v[38:39], v67 offset:0x2200
	ds_read_b64_tr_b16 v[40:41], v67 offset:0x2a00
	s_waitcnt lgkmcnt(6)
	ds_read_b64_tr_b16 v[42:43], v67 offset:0x3200
	ds_read_b64_tr_b16 v[44:45], v67 offset:0x3a00
	s_waitcnt lgkmcnt(6)
	v_mfma_f32_32x32x16_bf16 v[2:17], v[106:109], v[18:21], v[2:17]
	ds_read_b64_tr_b16 v[46:47], v67 offset:0x400
	ds_read_b64_tr_b16 v[48:49], v67 offset:0xc00
	s_waitcnt lgkmcnt(6)
	ds_read_b64_tr_b16 v[50:51], v67 offset:0x1400
	ds_read_b64_tr_b16 v[52:53], v67 offset:0x1c00
	s_waitcnt lgkmcnt(6)
	ds_read_b64_tr_b16 v[54:55], v67 offset:0x2400
	v_mfma_f32_32x32x16_bf16 v[2:17], v[102:105], v[22:25], v[2:17]
	ds_read_b64_tr_b16 v[56:57], v67 offset:0x2c00
	s_waitcnt lgkmcnt(6)
	ds_read_b64_tr_b16 v[58:59], v67 offset:0x3400
	ds_read_b64_tr_b16 v[60:61], v67 offset:0x3c00
	s_waitcnt lgkmcnt(6)
	ds_read_b64_tr_b16 v[62:63], v67 offset:0x600
	ds_read_b64_tr_b16 v[64:65], v67 offset:0xe00
	v_mfma_f32_32x32x16_bf16 v[2:17], v[94:97], v[26:29], v[2:17]
	s_waitcnt lgkmcnt(6)
	ds_read_b64_tr_b16 v[68:69], v67 offset:0x1600
	ds_read_b64_tr_b16 v[70:71], v67 offset:0x1e00
	s_waitcnt lgkmcnt(6)
	ds_read_b64_tr_b16 v[72:73], v67 offset:0x2600
	ds_read_b64_tr_b16 v[74:75], v67 offset:0x2e00
	s_waitcnt lgkmcnt(6)
	v_mfma_f32_32x32x16_bf16 v[18:33], v[110:113], v[30:33], 0
	ds_read_b64_tr_b16 v[76:77], v67 offset:0x3600
	ds_read_b64_tr_b16 v[78:79], v67 offset:0x3e00
	s_waitcnt lgkmcnt(6)
	s_waitcnt lgkmcnt(4)
	s_waitcnt lgkmcnt(2)
	v_add_u32_e32 v67, 0x4000, v67
	s_waitcnt lgkmcnt(0)
	v_mfma_f32_32x32x16_bf16 v[18:33], v[106:109], v[34:37], v[18:33]
	v_add_u32_e32 v144, s6, v66
	s_cselect_b32 s8, 1, -1
	s_cmp_lt_u32 s61, 2
	s_cselect_b64 s[0:1], -1, 0
	s_or_b64 s[6:7], s[14:15], s[0:1]
	v_lshl_add_u32 v156, v135, 8, 0
	v_lshlrev_b32_e32 v146, 2, v136
	v_mfma_f32_32x32x16_bf16 v[18:33], v[102:105], v[38:41], v[18:33]
	v_mov_b32_e32 v157, 0
	s_andn2_b64 vcc, exec, s[6:7]
	v_mfma_f32_32x32x16_bf16 v[18:33], v[94:97], v[42:45], v[18:33]
	v_mfma_f32_32x32x16_bf16 v[34:49], v[110:113], v[46:49], 0
	v_mfma_f32_32x32x16_bf16 v[34:49], v[106:109], v[50:53], v[34:49]
	v_mfma_f32_32x32x16_bf16 v[34:49], v[102:105], v[54:57], v[34:49]
	v_mfma_f32_32x32x16_bf16 v[34:49], v[94:97], v[58:61], v[34:49]
	v_mfma_f32_32x32x16_bf16 v[50:65], v[110:113], v[62:65], 0
	v_mfma_f32_32x32x16_bf16 v[50:65], v[106:109], v[68:71], v[50:65]
	ds_read_b64_tr_b16 v[68:69], v67 offset:0
	ds_read_b64_tr_b16 v[70:71], v67 offset:0x800
	v_mfma_f32_32x32x16_bf16 v[50:65], v[102:105], v[72:75], v[50:65]
	ds_read_b64_tr_b16 v[72:73], v67 offset:0x1000
	ds_read_b64_tr_b16 v[74:75], v67 offset:0x1800
	v_mfma_f32_32x32x16_bf16 v[50:65], v[94:97], v[76:79], v[50:65]
	ds_read_b64_tr_b16 v[76:77], v67 offset:0x2000
	ds_read_b64_tr_b16 v[78:79], v67 offset:0x2800
	ds_read_b64_tr_b16 v[114:115], v67 offset:0x3000
	ds_read_b64_tr_b16 v[116:117], v67 offset:0x3800
	s_waitcnt lgkmcnt(6)
	s_nop 0
	v_mfma_f32_32x32x16_bf16 v[2:17], v[98:101], v[68:71], v[2:17]
	ds_read_b64_tr_b16 v[68:69], v67 offset:0x200
	ds_read_b64_tr_b16 v[70:71], v67 offset:0xa00
	s_waitcnt lgkmcnt(6)
	s_nop 0
	v_mfma_f32_32x32x16_bf16 v[2:17], v[86:89], v[72:75], v[2:17]
	ds_read_b64_tr_b16 v[72:73], v67 offset:0x1200
	ds_read_b64_tr_b16 v[74:75], v67 offset:0x1a00
	s_waitcnt lgkmcnt(6)
	s_nop 0
	v_mfma_f32_32x32x16_bf16 v[2:17], v[90:93], v[76:79], v[2:17]
	ds_read_b64_tr_b16 v[76:77], v67 offset:0x2200
	ds_read_b64_tr_b16 v[78:79], v67 offset:0x2a00
	s_waitcnt lgkmcnt(6)
	s_nop 0
	v_mfma_f32_32x32x16_bf16 v[2:17], v[82:85], v[114:117], v[2:17]
	ds_read_b64_tr_b16 v[114:115], v67 offset:0x3200
	ds_read_b64_tr_b16 v[116:117], v67 offset:0x3a00
	s_waitcnt lgkmcnt(6)
	s_nop 0
	v_mfma_f32_32x32x16_bf16 v[18:33], v[98:101], v[68:71], v[18:33]
	ds_read_b64_tr_b16 v[68:69], v67 offset:0x400
	ds_read_b64_tr_b16 v[70:71], v67 offset:0xc00
	s_waitcnt lgkmcnt(6)
	s_nop 0
	v_mfma_f32_32x32x16_bf16 v[18:33], v[86:89], v[72:75], v[18:33]
	ds_read_b64_tr_b16 v[72:73], v67 offset:0x1400
	ds_read_b64_tr_b16 v[74:75], v67 offset:0x1c00
	s_waitcnt lgkmcnt(6)
	s_nop 0
	v_mfma_f32_32x32x16_bf16 v[18:33], v[90:93], v[76:79], v[18:33]
	ds_read_b64_tr_b16 v[76:77], v67 offset:0x2400
	ds_read_b64_tr_b16 v[78:79], v67 offset:0x2c00
	s_waitcnt lgkmcnt(6)
	s_nop 0
	v_mfma_f32_32x32x16_bf16 v[18:33], v[82:85], v[114:117], v[18:33]
	ds_read_b64_tr_b16 v[114:115], v67 offset:0x3400
	ds_read_b64_tr_b16 v[116:117], v67 offset:0x3c00
	s_waitcnt lgkmcnt(6)
	s_nop 0
	v_mfma_f32_32x32x16_bf16 v[34:49], v[98:101], v[68:71], v[34:49]
	ds_read_b64_tr_b16 v[68:69], v67 offset:0x600
	ds_read_b64_tr_b16 v[70:71], v67 offset:0xe00
	s_waitcnt lgkmcnt(6)
	s_nop 0
	v_mfma_f32_32x32x16_bf16 v[34:49], v[86:89], v[72:75], v[34:49]
	ds_read_b64_tr_b16 v[72:73], v67 offset:0x1600
	ds_read_b64_tr_b16 v[74:75], v67 offset:0x1e00
	s_waitcnt lgkmcnt(6)
	s_nop 0
	v_mfma_f32_32x32x16_bf16 v[34:49], v[90:93], v[76:79], v[34:49]
	ds_read_b64_tr_b16 v[76:77], v67 offset:0x2600
	ds_read_b64_tr_b16 v[78:79], v67 offset:0x2e00
	s_waitcnt lgkmcnt(6)
	s_nop 0
	v_mfma_f32_32x32x16_bf16 v[34:49], v[82:85], v[114:117], v[34:49]
	ds_read_b64_tr_b16 v[114:115], v67 offset:0x3600
	ds_read_b64_tr_b16 v[116:117], v67 offset:0x3e00
	s_waitcnt lgkmcnt(6)
	s_waitcnt lgkmcnt(4)
	s_waitcnt lgkmcnt(2)
	s_nop 0
	s_waitcnt lgkmcnt(0)
	v_mfma_f32_32x32x16_bf16 v[50:65], v[98:101], v[68:71], v[50:65]
	s_waitcnt lgkmcnt(0)
	v_mfma_f32_32x32x16_bf16 v[50:65], v[86:89], v[72:75], v[50:65]
	v_mfma_f32_32x32x16_bf16 v[50:65], v[90:93], v[76:79], v[50:65]
	ds_read_b128 v[66:69], v144
	ds_read_b128 v[70:73], v144 offset:32
	ds_read_b128 v[74:77], v144 offset:64
	ds_read_b128 v[78:81], v144 offset:96
	s_waitcnt lgkmcnt(3)
	v_pk_mul_f32 v[4:5], v[4:5], v[68:69]
	s_waitcnt lgkmcnt(2)
	v_pk_mul_f32 v[6:7], v[6:7], v[70:71]
	s_waitcnt lgkmcnt(1)
	v_pk_mul_f32 v[10:11], v[10:11], v[74:75]
	s_waitcnt lgkmcnt(0)
	v_pk_mul_f32 v[14:15], v[14:15], v[78:79]
	v_pk_mul_f32 v[16:17], v[16:17], v[80:81]
	v_mfma_f32_32x32x16_bf16 v[50:65], v[82:85], v[114:117], v[50:65]
	v_mul_f32_e64 v12, v12, v76
	v_mul_f32_e64 v13, v13, v77
	v_mul_f32_e64 v8, v8, v72
	v_mul_f32_e64 v9, v9, v73
	v_mul_f32_e64 v2, v2, v66
	v_mul_f32_e64 v3, v3, v67
	v_pk_mul_f32 v[30:31], v[30:31], v[78:79]
	v_pk_mul_f32 v[26:27], v[26:27], v[74:75]
	v_pk_mul_f32 v[22:23], v[22:23], v[70:71]
	v_pk_mul_f32 v[32:33], v[32:33], v[80:81]
	v_pk_mul_f32 v[28:29], v[28:29], v[76:77]
	v_pk_mul_f32 v[24:25], v[24:25], v[72:73]
	v_pk_mul_f32 v[20:21], v[20:21], v[68:69]
	v_pk_mul_f32 v[18:19], v[18:19], v[66:67]
	v_pk_mul_f32 v[46:47], v[46:47], v[78:79]
	v_pk_mul_f32 v[42:43], v[42:43], v[74:75]
	v_pk_mul_f32 v[38:39], v[38:39], v[70:71]
	v_pk_mul_f32 v[48:49], v[48:49], v[80:81]
	v_pk_mul_f32 v[44:45], v[44:45], v[76:77]
	v_pk_mul_f32 v[40:41], v[40:41], v[72:73]
	v_pk_mul_f32 v[36:37], v[36:37], v[68:69]
	v_pk_mul_f32 v[34:35], v[34:35], v[66:67]
	v_pk_mul_f32 v[64:65], v[64:65], v[80:81]
	v_pk_mul_f32 v[62:63], v[62:63], v[78:79]
	v_pk_mul_f32 v[60:61], v[60:61], v[76:77]
	v_pk_mul_f32 v[58:59], v[58:59], v[74:75]
	v_pk_mul_f32 v[56:57], v[56:57], v[72:73]
	v_pk_mul_f32 v[54:55], v[54:55], v[70:71]
	v_pk_mul_f32 v[52:53], v[52:53], v[68:69]
	v_pk_mul_f32 v[50:51], v[50:51], v[66:67]
	s_cbranch_vccnz .LBB0_681
	s_or_b64 s[6:7], s[14:15], s[24:25]
	v_mov_b32_e32 v117, 0
	s_andn2_b64 vcc, exec, s[6:7]
	v_mov_b32_e32 v121, 0
	v_mov_b32_e32 v122, 0
	v_mov_b32_e32 v123, 0
	v_mov_b32_e32 v124, 0
	v_mov_b32_e32 v125, 0
	v_mov_b32_e32 v118, 0
	v_mov_b32_e32 v119, 0
	v_mov_b32_e32 v126, 0
	v_mov_b32_e32 v127, 0
	v_mov_b32_e32 v128, 0
	v_mov_b32_e32 v129, 0
	v_mov_b32_e32 v130, 0
	v_mov_b32_e32 v131, 0
	v_mov_b32_e32 v132, 0
	v_mov_b32_e32 v133, 0
	s_cbranch_vccnz .LBB0_677
	v_add_u32_e32 v66, v156, v147
	ds_read_b128 v[66:69], v66 offset:32768
	v_add_u32_e32 v114, v156, v148
	ds_read_b128 v[118:121], v114 offset:32768
	v_add_u32_e32 v228, v156, v149
	ds_read_b128 v[228:231], v228 offset:32768
	v_add_u32_e32 v232, v156, v150
	ds_read_b128 v[232:235], v232 offset:32768
	v_add_u32_e32 v236, v156, v151
	ds_read_b128 v[236:239], v236 offset:32768
	v_add_u32_e32 v240, v156, v152
	ds_read_b128 v[240:243], v240 offset:32768
	v_add_u32_e32 v244, v156, v153
	ds_read_b128 v[244:247], v244 offset:32768
	v_add_u32_e32 v248, v156, v155
	ds_read_b128 v[248:251], v248 offset:32768
	s_waitcnt lgkmcnt(7)
	v_mfma_f32_32x32x16_bf16 v[66:81], v[66:69], v[110:113], 0
	s_waitcnt lgkmcnt(6)
	v_mfma_f32_32x32x16_bf16 v[66:81], v[118:121], v[106:109], v[66:81]
	s_waitcnt lgkmcnt(5)
	v_mfma_f32_32x32x16_bf16 v[66:81], v[228:231], v[102:105], v[66:81]
	s_waitcnt lgkmcnt(4)
	v_mfma_f32_32x32x16_bf16 v[66:81], v[232:235], v[94:97], v[66:81]
	s_waitcnt lgkmcnt(3)
	v_mfma_f32_32x32x16_bf16 v[66:81], v[236:239], v[98:101], v[66:81]
	s_waitcnt lgkmcnt(2)
	v_mfma_f32_32x32x16_bf16 v[66:81], v[240:243], v[86:89], v[66:81]
	s_waitcnt lgkmcnt(1)
	v_mfma_f32_32x32x16_bf16 v[66:81], v[244:247], v[90:93], v[66:81]
	s_waitcnt lgkmcnt(0)
	v_mfma_f32_32x32x16_bf16 v[66:81], v[248:251], v[82:85], v[66:81]
	v_sub_u32_e32 v114, v141, v146
	v_mul_i32_i24_e32 v114, s8, v114
	v_ashrrev_i32_e32 v114, 31, v114
	v_cvt_f32_i32_e32 v115, v114
	v_lshl_add_u32 v114, v146, 2, s94
	ds_read_b128 v[122:125], v114 offset:512
	ds_read_b128 v[118:121], v114 offset:544
	s_waitcnt lgkmcnt(1)
	v_add_f32_e32 v116, v145, v122
	v_fmac_f32_e32 v116, 0x7149f2ca, v115
	v_mul_f32_e32 v115, 0x3fb8aa3b, v116
	v_exp_f32_e32 v122, v115
	v_or_b32_e32 v115, 1, v146
	v_sub_u32_e32 v115, v141, v115
	v_mul_i32_i24_e32 v115, s8, v115
	v_ashrrev_i32_e32 v115, 31, v115
	v_cvt_f32_i32_e32 v115, v115
	v_add_f32_e32 v116, v145, v123
	v_fmac_f32_e32 v116, 0x7149f2ca, v115
	v_mul_f32_e32 v115, 0x3fb8aa3b, v116
	v_exp_f32_e32 v123, v115
	v_add_f32_e32 v116, v145, v125
	v_pk_mul_f32 v[122:123], v[66:67], v[122:123]
	s_nop 0
	v_add_f32_e32 v66, 0, v122
	v_add_f32_e32 v115, v66, v123
	v_or_b32_e32 v66, 2, v146
	v_sub_u32_e32 v66, v141, v66
	v_mul_i32_i24_e32 v66, s8, v66
	v_ashrrev_i32_e32 v66, 31, v66
	v_cvt_f32_i32_e32 v66, v66
	v_add_f32_e32 v67, v145, v124
	v_fmac_f32_e32 v67, 0x7149f2ca, v66
	v_mul_f32_e32 v66, 0x3fb8aa3b, v67
	v_or_b32_e32 v67, 3, v146
	v_sub_u32_e32 v67, v141, v67
	v_mul_i32_i24_e32 v67, s8, v67
	v_ashrrev_i32_e32 v67, 31, v67
	v_cvt_f32_i32_e32 v67, v67
	v_exp_f32_e32 v66, v66
	v_fmac_f32_e32 v116, 0x7149f2ca, v67
	v_mul_f32_e32 v67, 0x3fb8aa3b, v116
	v_exp_f32_e32 v67, v67
	s_nop 0
	v_pk_mul_f32 v[124:125], v[68:69], v[66:67]
	s_nop 0
	v_add_f32_e32 v66, v115, v124
	v_add_f32_e32 v68, v66, v125
	v_or_b32_e32 v66, 8, v146
	v_sub_u32_e32 v66, v141, v66
	v_mul_i32_i24_e32 v66, s8, v66
	v_ashrrev_i32_e32 v66, 31, v66
	v_cvt_f32_i32_e32 v66, v66
	s_waitcnt lgkmcnt(0)
	v_add_f32_e32 v67, v145, v118
	v_add_f32_e32 v69, v145, v119
	v_fmac_f32_e32 v67, 0x7149f2ca, v66
	v_mul_f32_e32 v66, 0x3fb8aa3b, v67
	v_or_b32_e32 v67, 9, v146
	v_sub_u32_e32 v67, v141, v67
	v_mul_i32_i24_e32 v67, s8, v67
	v_ashrrev_i32_e32 v67, 31, v67
	v_cvt_f32_i32_e32 v67, v67
	v_exp_f32_e32 v66, v66
	v_fmac_f32_e32 v69, 0x7149f2ca, v67
	v_mul_f32_e32 v67, 0x3fb8aa3b, v69
	v_exp_f32_e32 v67, v67
	v_add_f32_e32 v69, v145, v121
	v_pk_mul_f32 v[118:119], v[70:71], v[66:67]
	s_nop 0
	v_add_f32_e32 v66, v68, v118
	v_add_f32_e32 v68, v66, v119
	v_or_b32_e32 v66, 10, v146
	v_sub_u32_e32 v66, v141, v66
	v_mul_i32_i24_e32 v66, s8, v66
	v_ashrrev_i32_e32 v66, 31, v66
	v_cvt_f32_i32_e32 v66, v66
	v_add_f32_e32 v67, v145, v120
	v_fmac_f32_e32 v67, 0x7149f2ca, v66
	v_mul_f32_e32 v66, 0x3fb8aa3b, v67
	v_or_b32_e32 v67, 11, v146
	v_sub_u32_e32 v67, v141, v67
	v_mul_i32_i24_e32 v67, s8, v67
	v_ashrrev_i32_e32 v67, 31, v67
	v_cvt_f32_i32_e32 v67, v67
	v_exp_f32_e32 v66, v66
	v_fmac_f32_e32 v69, 0x7149f2ca, v67
	v_mul_f32_e32 v67, 0x3fb8aa3b, v69
	v_exp_f32_e32 v67, v67
	s_nop 0
	v_pk_mul_f32 v[126:127], v[72:73], v[66:67]
	s_nop 0
	v_add_f32_e32 v66, v68, v126
	v_add_f32_e32 v70, v66, v127
	v_or_b32_e32 v66, 16, v146
	v_sub_u32_e32 v66, v141, v66
	v_mul_i32_i24_e32 v66, s8, v66
	v_ashrrev_i32_e32 v66, 31, v66
	v_cvt_f32_i32_e32 v71, v66
	ds_read_b128 v[66:69], v114 offset:576
	s_waitcnt lgkmcnt(0)
	v_add_f32_e32 v66, v145, v66
	v_fmac_f32_e32 v66, 0x7149f2ca, v71
	v_or_b32_e32 v71, 17, v146
	v_sub_u32_e32 v71, v141, v71
	v_mul_i32_i24_e32 v71, s8, v71
	v_ashrrev_i32_e32 v71, 31, v71
	v_cvt_f32_i32_e32 v71, v71
	v_add_f32_e32 v67, v145, v67
	v_mul_f32_e32 v66, 0x3fb8aa3b, v66
	v_exp_f32_e32 v66, v66
	v_fmac_f32_e32 v67, 0x7149f2ca, v71
	v_mul_f32_e32 v67, 0x3fb8aa3b, v67
	v_exp_f32_e32 v67, v67
	s_nop 0
	v_pk_mul_f32 v[128:129], v[74:75], v[66:67]
	s_nop 0
	v_add_f32_e32 v66, v70, v128
	v_add_f32_e32 v70, v66, v129
	v_or_b32_e32 v66, 18, v146
	v_sub_u32_e32 v66, v141, v66
	v_mul_i32_i24_e32 v66, s8, v66
	v_ashrrev_i32_e32 v66, 31, v66
	v_cvt_f32_i32_e32 v66, v66
	v_add_f32_e32 v67, v145, v68
	v_add_f32_e32 v68, v145, v69
	v_fmac_f32_e32 v67, 0x7149f2ca, v66
	v_mul_f32_e32 v66, 0x3fb8aa3b, v67
	v_or_b32_e32 v67, 19, v146
	v_sub_u32_e32 v67, v141, v67
	v_mul_i32_i24_e32 v67, s8, v67
	v_ashrrev_i32_e32 v67, 31, v67
	v_cvt_f32_i32_e32 v67, v67
	v_exp_f32_e32 v66, v66
	v_fmac_f32_e32 v68, 0x7149f2ca, v67
	v_mul_f32_e32 v67, 0x3fb8aa3b, v68
	v_exp_f32_e32 v67, v67
	s_nop 0
	v_pk_mul_f32 v[130:131], v[76:77], v[66:67]
	s_nop 0
	v_add_f32_e32 v66, v70, v130
	v_add_f32_e32 v70, v66, v131
	v_or_b32_e32 v66, 24, v146
	v_sub_u32_e32 v66, v141, v66
	v_mul_i32_i24_e32 v66, s8, v66
	v_ashrrev_i32_e32 v66, 31, v66
	v_cvt_f32_i32_e32 v71, v66
	ds_read_b128 v[66:69], v114 offset:608
	s_waitcnt lgkmcnt(0)
	v_add_f32_e32 v66, v145, v66
	v_fmac_f32_e32 v66, 0x7149f2ca, v71
	v_or_b32_e32 v71, 25, v146
	v_sub_u32_e32 v71, v141, v71
	v_mul_i32_i24_e32 v71, s8, v71
	v_ashrrev_i32_e32 v71, 31, v71
	v_cvt_f32_i32_e32 v71, v71
	v_add_f32_e32 v67, v145, v67
	v_mul_f32_e32 v66, 0x3fb8aa3b, v66
	v_exp_f32_e32 v66, v66
	v_fmac_f32_e32 v67, 0x7149f2ca, v71
	v_mul_f32_e32 v67, 0x3fb8aa3b, v67
	v_exp_f32_e32 v67, v67
	s_nop 0
	v_pk_mul_f32 v[132:133], v[78:79], v[66:67]
	s_nop 0
	v_add_f32_e32 v66, v70, v132
	v_add_f32_e32 v70, v66, v133
	v_or_b32_e32 v66, 26, v146
	v_sub_u32_e32 v66, v141, v66
	v_mul_i32_i24_e32 v66, s8, v66
	v_ashrrev_i32_e32 v66, 31, v66
	v_cvt_f32_i32_e32 v66, v66
	v_add_f32_e32 v67, v145, v68
	v_add_f32_e32 v68, v145, v69
	v_fmac_f32_e32 v67, 0x7149f2ca, v66
	v_mul_f32_e32 v66, 0x3fb8aa3b, v67
	v_or_b32_e32 v67, 27, v146
	v_sub_u32_e32 v67, v141, v67
	v_mul_i32_i24_e32 v67, s8, v67
	v_ashrrev_i32_e32 v67, 31, v67
	v_cvt_f32_i32_e32 v67, v67
	v_exp_f32_e32 v66, v66
	v_fmac_f32_e32 v68, 0x7149f2ca, v67
	v_mul_f32_e32 v67, 0x3fb8aa3b, v68
	v_exp_f32_e32 v67, v67
	s_nop 0
	v_pk_mul_f32 v[66:67], v[80:81], v[66:67]
	s_nop 0
	v_add_f32_e32 v68, v70, v66
	v_add_f32_e32 v157, v68, v67
	v_cvt_pk_bf16_f32 v121, v66, v67
.LBB0_677:
	s_cmp_lg_u32 s61, 0
	s_cselect_b64 s[6:7], -1, 0
	v_cndmask_b32_e64 v66, 0, 1, s[6:7]
	v_cndmask_b32_e64 v67, 0, 1, s[0:1]
	v_cndmask_b32_e64 v66, v67, v66, s[14:15]
	v_and_b32_e32 v66, 1, v66
	v_cmp_eq_u32_e32 vcc, 0, v66
	s_cbranch_vccnz .LBB0_679
	v_add_u32_e32 v66, v156, v147
	ds_read_b128 v[66:69], v66 offset:40960
	v_add_u32_e32 v114, v156, v148
	ds_read_b128 v[114:117], v114 offset:40960
	v_or_b32_e32 v120, 32, v146
	v_add_u32_e32 v228, v156, v149
	ds_read_b128 v[228:231], v228 offset:40960
	v_add_u32_e32 v232, v156, v150
	ds_read_b128 v[232:235], v232 offset:40960
	v_add_u32_e32 v236, v156, v151
	ds_read_b128 v[236:239], v236 offset:40960
	v_add_u32_e32 v240, v156, v152
	ds_read_b128 v[240:243], v240 offset:40960
	v_add_u32_e32 v244, v156, v153
	ds_read_b128 v[244:247], v244 offset:40960
	v_add_u32_e32 v248, v156, v155
	ds_read_b128 v[248:251], v248 offset:40960
	s_waitcnt lgkmcnt(7)
	v_mfma_f32_32x32x16_bf16 v[66:81], v[66:69], v[110:113], 0
	s_waitcnt lgkmcnt(6)
	v_mfma_f32_32x32x16_bf16 v[66:81], v[114:117], v[106:109], v[66:81]
	s_waitcnt lgkmcnt(5)
	v_mfma_f32_32x32x16_bf16 v[66:81], v[228:231], v[102:105], v[66:81]
	s_waitcnt lgkmcnt(4)
	v_mfma_f32_32x32x16_bf16 v[66:81], v[232:235], v[94:97], v[66:81]
	s_waitcnt lgkmcnt(3)
	v_mfma_f32_32x32x16_bf16 v[66:81], v[236:239], v[98:101], v[66:81]
	s_waitcnt lgkmcnt(2)
	v_mfma_f32_32x32x16_bf16 v[66:81], v[240:243], v[86:89], v[66:81]
	s_waitcnt lgkmcnt(1)
	v_mfma_f32_32x32x16_bf16 v[66:81], v[244:247], v[90:93], v[66:81]
	s_waitcnt lgkmcnt(0)
	v_mfma_f32_32x32x16_bf16 v[66:81], v[248:251], v[82:85], v[66:81]
	v_sub_u32_e32 v114, v141, v120
	v_mul_i32_i24_e32 v114, s8, v114
	v_ashrrev_i32_e32 v114, 31, v114
	v_lshl_add_u32 v120, v146, 2, s94
	v_cvt_f32_i32_e32 v162, v114
	ds_read_b128 v[158:161], v120 offset:640
	ds_read_b128 v[114:117], v120 offset:672
	s_waitcnt lgkmcnt(1)
	v_add_f32_e32 v158, v145, v158
	v_fmac_f32_e32 v158, 0x7149f2ca, v162
	v_or_b32_e32 v162, 33, v146
	v_sub_u32_e32 v162, v141, v162
	v_mul_i32_i24_e32 v162, s8, v162
	v_ashrrev_i32_e32 v162, 31, v162
	v_cvt_f32_i32_e32 v162, v162
	v_add_f32_e32 v159, v145, v159
	v_mul_f32_e32 v158, 0x3fb8aa3b, v158
	v_exp_f32_e32 v158, v158
	v_fmac_f32_e32 v159, 0x7149f2ca, v162
	v_mul_f32_e32 v159, 0x3fb8aa3b, v159
	v_exp_f32_e32 v159, v159
	s_waitcnt lgkmcnt(0)
	v_add_f32_e32 v114, v145, v114
	v_add_f32_e32 v115, v145, v115
	v_pk_mul_f32 v[66:67], v[66:67], v[158:159]
	v_or_b32_e32 v158, 34, v146
	v_sub_u32_e32 v158, v141, v158
	v_mul_i32_i24_e32 v158, s8, v158
	v_ashrrev_i32_e32 v158, 31, v158
	v_cvt_f32_i32_e32 v158, v158
	v_add_f32_e32 v159, v145, v160
	v_add_f32_e32 v160, v145, v161
	v_add_f32_e32 v157, v157, v66
	v_fmac_f32_e32 v159, 0x7149f2ca, v158
	v_mul_f32_e32 v158, 0x3fb8aa3b, v159
	v_or_b32_e32 v159, 35, v146
	v_sub_u32_e32 v159, v141, v159
	v_mul_i32_i24_e32 v159, s8, v159
	v_ashrrev_i32_e32 v159, 31, v159
	v_cvt_f32_i32_e32 v159, v159
	v_exp_f32_e32 v158, v158
	v_add_f32_e32 v157, v157, v67
	v_fmac_f32_e32 v160, 0x7149f2ca, v159
	v_mul_f32_e32 v159, 0x3fb8aa3b, v160
	v_exp_f32_e32 v159, v159
	s_nop 0
	v_pk_mul_f32 v[68:69], v[68:69], v[158:159]
	v_or_b32_e32 v158, 40, v146
	v_sub_u32_e32 v158, v141, v158
	v_mul_i32_i24_e32 v158, s8, v158
	v_ashrrev_i32_e32 v158, 31, v158
	v_cvt_f32_i32_e32 v158, v158
	v_add_f32_e32 v157, v157, v68
	v_add_f32_e32 v157, v157, v69
	v_fmac_f32_e32 v114, 0x7149f2ca, v158
	v_or_b32_e32 v158, 41, v146
	v_sub_u32_e32 v158, v141, v158
	v_mul_i32_i24_e32 v158, s8, v158
	v_ashrrev_i32_e32 v158, 31, v158
	v_cvt_f32_i32_e32 v158, v158
	v_mul_f32_e32 v114, 0x3fb8aa3b, v114
	v_exp_f32_e32 v114, v114
	v_fmac_f32_e32 v115, 0x7149f2ca, v158
	v_mul_f32_e32 v115, 0x3fb8aa3b, v115
	v_exp_f32_e32 v115, v115
	s_nop 0
	v_pk_mul_f32 v[70:71], v[70:71], v[114:115]
	s_nop 0
	v_add_f32_e32 v114, v157, v70
	v_add_f32_e32 v157, v114, v71
	v_or_b32_e32 v114, 42, v146
	v_sub_u32_e32 v114, v141, v114
	v_mul_i32_i24_e32 v114, s8, v114
	v_ashrrev_i32_e32 v114, 31, v114
	v_cvt_f32_i32_e32 v114, v114
	v_add_f32_e32 v115, v145, v116
	v_add_f32_e32 v116, v145, v117
	v_fmac_f32_e32 v115, 0x7149f2ca, v114
	v_mul_f32_e32 v114, 0x3fb8aa3b, v115
	v_or_b32_e32 v115, 43, v146
	v_sub_u32_e32 v115, v141, v115
	v_mul_i32_i24_e32 v115, s8, v115
	v_ashrrev_i32_e32 v115, 31, v115
	v_cvt_f32_i32_e32 v115, v115
	v_exp_f32_e32 v114, v114
	v_fmac_f32_e32 v116, 0x7149f2ca, v115
	v_mul_f32_e32 v115, 0x3fb8aa3b, v116
	v_exp_f32_e32 v115, v115
	s_nop 0
	v_pk_mul_f32 v[72:73], v[72:73], v[114:115]
	s_nop 0
	v_add_f32_e32 v114, v157, v72
	v_add_f32_e32 v157, v114, v73
	v_or_b32_e32 v114, 48, v146
	v_sub_u32_e32 v114, v141, v114
	v_mul_i32_i24_e32 v114, s8, v114
	v_ashrrev_i32_e32 v114, 31, v114
	v_cvt_f32_i32_e32 v158, v114
	ds_read_b128 v[114:117], v120 offset:704
	s_waitcnt lgkmcnt(0)
	v_add_f32_e32 v114, v145, v114
	v_fmac_f32_e32 v114, 0x7149f2ca, v158
	v_or_b32_e32 v158, 49, v146
	v_sub_u32_e32 v158, v141, v158
	v_mul_i32_i24_e32 v158, s8, v158
	v_ashrrev_i32_e32 v158, 31, v158
	v_cvt_f32_i32_e32 v158, v158
	v_add_f32_e32 v115, v145, v115
	v_mul_f32_e32 v114, 0x3fb8aa3b, v114
	v_exp_f32_e32 v114, v114
	v_fmac_f32_e32 v115, 0x7149f2ca, v158
	v_mul_f32_e32 v115, 0x3fb8aa3b, v115
	v_exp_f32_e32 v115, v115
	s_nop 0
	v_pk_mul_f32 v[74:75], v[74:75], v[114:115]
	s_nop 0
	v_add_f32_e32 v114, v157, v74
	v_add_f32_e32 v157, v114, v75
	v_or_b32_e32 v114, 50, v146
	v_sub_u32_e32 v114, v141, v114
	v_mul_i32_i24_e32 v114, s8, v114
	v_ashrrev_i32_e32 v114, 31, v114
	v_cvt_f32_i32_e32 v114, v114
	v_add_f32_e32 v115, v145, v116
	v_add_f32_e32 v116, v145, v117
	v_fmac_f32_e32 v115, 0x7149f2ca, v114
	v_mul_f32_e32 v114, 0x3fb8aa3b, v115
	v_or_b32_e32 v115, 51, v146
	v_sub_u32_e32 v115, v141, v115
	v_mul_i32_i24_e32 v115, s8, v115
	v_ashrrev_i32_e32 v115, 31, v115
	v_cvt_f32_i32_e32 v115, v115
	v_exp_f32_e32 v114, v114
	v_fmac_f32_e32 v116, 0x7149f2ca, v115
	v_mul_f32_e32 v115, 0x3fb8aa3b, v116
	v_exp_f32_e32 v115, v115
	s_nop 0
	v_pk_mul_f32 v[76:77], v[76:77], v[114:115]
	s_nop 0
	v_add_f32_e32 v114, v157, v76
	v_add_f32_e32 v157, v114, v77
	v_or_b32_e32 v114, 56, v146
	v_sub_u32_e32 v114, v141, v114
	v_mul_i32_i24_e32 v114, s8, v114
	v_ashrrev_i32_e32 v114, 31, v114
	v_cvt_f32_i32_e32 v158, v114
	ds_read_b128 v[114:117], v120 offset:736
	v_or_b32_e32 v120, 57, v146
	v_sub_u32_e32 v120, v141, v120
	v_mul_i32_i24_e32 v120, s8, v120
	v_ashrrev_i32_e32 v120, 31, v120
	v_cvt_f32_i32_e32 v120, v120
	s_waitcnt lgkmcnt(0)
	v_add_f32_e32 v114, v145, v114
	v_add_f32_e32 v115, v145, v115
	v_fmac_f32_e32 v114, 0x7149f2ca, v158
	v_fmac_f32_e32 v115, 0x7149f2ca, v120
	v_mul_f32_e32 v114, 0x3fb8aa3b, v114
	v_mul_f32_e32 v115, 0x3fb8aa3b, v115
	v_exp_f32_e32 v114, v114
	v_exp_f32_e32 v115, v115
	s_nop 0
	v_pk_mul_f32 v[78:79], v[78:79], v[114:115]
	s_nop 0
	v_add_f32_e32 v114, v157, v78
	v_add_f32_e32 v120, v114, v79
	v_or_b32_e32 v114, 58, v146
	v_sub_u32_e32 v114, v141, v114
	v_mul_i32_i24_e32 v114, s8, v114
	v_ashrrev_i32_e32 v114, 31, v114
	v_cvt_f32_i32_e32 v114, v114
	v_add_f32_e32 v115, v145, v116
	v_add_f32_e32 v116, v145, v117
	v_fmac_f32_e32 v115, 0x7149f2ca, v114
	v_mul_f32_e32 v114, 0x3fb8aa3b, v115
	v_or_b32_e32 v115, 59, v146
	v_sub_u32_e32 v115, v141, v115
	v_mul_i32_i24_e32 v115, s8, v115
	v_ashrrev_i32_e32 v115, 31, v115
	v_cvt_f32_i32_e32 v115, v115
	v_exp_f32_e32 v114, v114
	v_fmac_f32_e32 v116, 0x7149f2ca, v115
	v_mul_f32_e32 v115, 0x3fb8aa3b, v116
	v_exp_f32_e32 v115, v115
	s_nop 0
	v_pk_mul_f32 v[80:81], v[80:81], v[114:115]
	s_nop 0
	v_add_f32_e32 v114, v120, v80
	v_add_f32_e32 v157, v114, v81
	v_cvt_pk_bf16_f32 v117, v80, v81
	s_branch .LBB0_680
